# P7 EpiBf2/EpiBf3 epilogues: gate loads requested ahead into v180-243 with counted vmcnt waits instead of per-load vmcnt(0)
# speedup vs baseline: 1.0094x; 1.0013x over previous
; #define LAS __attribute__((address_space(3)))
; __device__ __forceinline__ unsigned cvt_pk_bf16(float lo, float hi) { f32x2_t v = {lo, hi}; bf16x2_t b = __builtin_convertvector(v, bf16x2_t); return __builtin_bit_cast(unsigned, b); }
; __device__ __forceinline__ float bflo(unsigned w) { return __uint_as_float(w << 16); }
; __device__ __forceinline__ float bfhi(unsigned w) { return __uint_as_float(w & 0xffff0000u); }
; __device__ __forceinline__ float sigm(float x) { return __builtin_amdgcn_rcpf(1.0f + __expf(-x)); }
;     __device__ __forceinline__ void operator()(AccRef acc, const pg8::Unit& u, int, int, int, int) const {
;     ...
;         for (int ai = 0; ai < 2; ++ai)
; #pragma unroll
;             for (int m = 0; m < 4; ++m) {
;                 const int row = row0 + ai * 128 + m * 16; float rs = 1.f;
;                 if (MODE == 1 || MODE == 4) rs = ((const LAS float*)((LAS unsigned char*)g_lds + pg8::RSL_OFF))[wid * 128 + ai * 64 + m * 16 + fr];
; #pragma unroll
;                 for (int bj = 0; bj < 2; ++bj) {
;                     const int col = col0 + bj * 128; float o[8];
; #pragma unroll
;                     for (int n = 0; n < 2; ++n)
; #pragma unroll
;                         for (int j = 0; j < 4; ++j) o[n * 4 + j] = acc[ai][bj][m][n][j] * rs;
;                     if (sg) {
; #pragma unroll
;                         for (int j = 0; j < 8; ++j) o[j] = sigm(o[j]); }
;                     if (MODE == 2 || MODE == 3) {
;                         const v4u x = *(const v4u*)(a1 + (size_t)row * ld1 + col);
;                         float xf[8] = {bflo(x.x), bfhi(x.x), bflo(x.y), bfhi(x.y), bflo(x.z), bfhi(x.z), bflo(x.w), bfhi(x.w)};
;                         if (MODE == 2) {
; #pragma unroll
;                             for (int j = 0; j < 8; ++j) o[j] *= xf[j]; }
;                         else { const v4u y = *(const v4u*)(a2 + (size_t)row * ld2 + col);
;                             float yf[8] = {bflo(y.x), bfhi(y.x), bflo(y.y), bfhi(y.y), bflo(y.z), bfhi(y.z), bflo(y.w), bfhi(y.w)};
; #pragma unroll
;                             for (int j = 0; j < 8; ++j) o[j] = xf[j] + yf[j] * o[j]; }
;                     }
;                     v4u w; w.x = cvt_pk_bf16(o[0], o[1]); w.y = cvt_pk_bf16(o[2], o[3]); w.z = cvt_pk_bf16(o[4], o[5]); w.w = cvt_pk_bf16(o[6], o[7]);
;                     *(v4u*)(O + (size_t)row * ldo + col) = w;
.LBB0_417:
	v_mov_b32_e32 v141, v155
	s_lshl_b32 s3, s39, 8
	v_readfirstlane_b32 s0, v141
	s_ashr_i32 s2, s0, 2
	s_lshr_b32 s0, s0, 1
	s_and_b32 s0, s0, 0x60
	s_lshl_b32 s1, s38, 8
	s_or_b32 s0, s0, s3
	v_lshrrev_b32_e32 v140, 1, v141
	v_and_or_b32 v140, v140, 24, s0
	v_and_or_b32 v141, v141, 15, s1
	v_readlane_b32 s0, v254, 43
	s_andn2_b32 s2, s2, 63
	v_readlane_b32 s1, v254, 44
	v_add_u32_e32 v142, s2, v141
	v_ashrrev_i32_e32 v141, 31, v140
	v_mov_b64_e32 v[144:145], s[0:1]
	v_mad_i64_i32 v[148:149], s[0:1], v142, s68, v[144:145]
	v_lshlrev_b64 v[140:141], 1, v[140:141]
	v_lshl_add_u64 v[152:153], v[148:149], 0, v[140:141]
	v_mov_b32_e32 v248, v152
	v_mov_b32_e32 v249, v153
	global_load_dwordx4 v[180:183], v[248:249], off
	global_load_dwordx4 v[184:187], v[248:249], off offset:256
	v_mov_b32_e32 v244, 0x2c000
	v_mov_b32_e32 v245, 0
	v_lshl_add_u64 v[246:247], v[248:249], 0, v[244:245]
	global_load_dwordx4 v[188:191], v[246:247], off
	global_load_dwordx4 v[192:195], v[246:247], off offset:256
	v_mov_b32_e32 v244, 0x58000
	v_mov_b32_e32 v245, 0
	v_lshl_add_u64 v[246:247], v[248:249], 0, v[244:245]
	global_load_dwordx4 v[196:199], v[246:247], off
	global_load_dwordx4 v[200:203], v[246:247], off offset:256
	v_mov_b32_e32 v244, 0x84000
	v_mov_b32_e32 v245, 0
	v_lshl_add_u64 v[246:247], v[248:249], 0, v[244:245]
	global_load_dwordx4 v[204:207], v[246:247], off
	global_load_dwordx4 v[208:211], v[246:247], off offset:256
	v_mov_b32_e32 v244, 0x160000
	v_mov_b32_e32 v245, 0
	v_lshl_add_u64 v[246:247], v[248:249], 0, v[244:245]
	global_load_dwordx4 v[212:215], v[246:247], off
	global_load_dwordx4 v[216:219], v[246:247], off offset:256
	v_mov_b32_e32 v244, 0x18c000
	v_mov_b32_e32 v245, 0
	v_lshl_add_u64 v[246:247], v[248:249], 0, v[244:245]
	global_load_dwordx4 v[220:223], v[246:247], off
	global_load_dwordx4 v[224:227], v[246:247], off offset:256
	v_mov_b32_e32 v244, 0x1b8000
	v_mov_b32_e32 v245, 0
	v_lshl_add_u64 v[246:247], v[248:249], 0, v[244:245]
	global_load_dwordx4 v[228:231], v[246:247], off
	global_load_dwordx4 v[232:235], v[246:247], off offset:256
	v_mov_b32_e32 v244, 0x1e4000
	v_mov_b32_e32 v245, 0
	v_lshl_add_u64 v[246:247], v[248:249], 0, v[244:245]
	global_load_dwordx4 v[236:239], v[246:247], off
	global_load_dwordx4 v[240:243], v[246:247], off offset:256
	v_ashrrev_i32_e32 v143, 31, v142
	s_and_b64 vcc, exec, s[6:7]
	s_waitcnt vmcnt(15)
	v_lshlrev_b32_e32 v156, 16, v180
	v_and_b32_e32 v157, 0xffff0000, v180
	v_lshlrev_b32_e32 v148, 16, v181
	v_and_b32_e32 v149, 0xffff0000, v181
	v_pk_mul_f32 v[128:129], v[128:129], v[148:149]
	v_lshlrev_b32_e32 v148, 16, v182
	v_and_b32_e32 v149, 0xffff0000, v182
	v_pk_mul_f32 v[126:127], v[126:127], v[156:157]
	v_pk_mul_f32 v[148:149], v[122:123], v[148:149]
	v_lshlrev_b32_e32 v122, 16, v183
	v_and_b32_e32 v123, 0xffff0000, v183
	v_pk_mul_f32 v[150:151], v[124:125], v[122:123]
	v_cvt_pk_bf16_f32 v122, v126, v127
	v_lshlrev_b64 v[126:127], 11, v[142:143]
	v_lshl_add_u64 v[126:127], s[76:77], 0, v[126:127]
	v_cvt_pk_bf16_f32 v123, v128, v129
	v_cvt_pk_bf16_f32 v124, v148, v149
	v_cvt_pk_bf16_f32 v125, v150, v151
	v_lshl_add_u64 v[126:127], v[126:127], 0, v[140:141]
	global_store_dwordx4 v[126:127], v[122:125], off
	s_waitcnt vmcnt(15)
	v_lshlrev_b32_e32 v128, 16, v184
	v_and_b32_e32 v129, 0xffff0000, v184
	v_lshlrev_b32_e32 v122, 16, v185
	v_and_b32_e32 v123, 0xffff0000, v185
	v_pk_mul_f32 v[120:121], v[120:121], v[122:123]
	v_lshlrev_b32_e32 v122, 16, v186
	v_and_b32_e32 v123, 0xffff0000, v186
	v_pk_mul_f32 v[122:123], v[114:115], v[122:123]
	v_lshlrev_b32_e32 v114, 16, v187
	v_and_b32_e32 v115, 0xffff0000, v187
	v_pk_mul_f32 v[118:119], v[118:119], v[128:129]
	v_pk_mul_f32 v[124:125], v[116:117], v[114:115]
	v_cvt_pk_bf16_f32 v114, v118, v119
	v_cvt_pk_bf16_f32 v115, v120, v121
	v_cvt_pk_bf16_f32 v116, v122, v123
	v_cvt_pk_bf16_f32 v117, v124, v125
	v_or_b32_e32 v118, 16, v142
	global_store_dwordx4 v[126:127], v[114:117], off offset:256
	v_ashrrev_i32_e32 v119, 31, v118
	s_nop 0
	v_mad_i64_i32 v[114:115], s[0:1], v118, s68, v[144:145]
	v_lshl_add_u64 v[120:121], v[114:115], 0, v[140:141]
	s_waitcnt vmcnt(15)
	v_lshlrev_b32_e32 v122, 16, v188
	v_and_b32_e32 v123, 0xffff0000, v188
	v_lshlrev_b32_e32 v114, 16, v189
	v_and_b32_e32 v115, 0xffff0000, v189
	v_pk_mul_f32 v[112:113], v[112:113], v[114:115]
	v_lshlrev_b32_e32 v114, 16, v190
	v_and_b32_e32 v115, 0xffff0000, v190
	v_pk_mul_f32 v[110:111], v[110:111], v[122:123]
	v_pk_mul_f32 v[114:115], v[106:107], v[114:115]
	v_lshlrev_b32_e32 v106, 16, v191
	v_and_b32_e32 v107, 0xffff0000, v191
	v_pk_mul_f32 v[116:117], v[108:109], v[106:107]
	v_cvt_pk_bf16_f32 v106, v110, v111
	v_lshlrev_b64 v[110:111], 11, v[118:119]
	v_lshl_add_u64 v[110:111], s[76:77], 0, v[110:111]
	v_cvt_pk_bf16_f32 v107, v112, v113
	v_cvt_pk_bf16_f32 v108, v114, v115
	v_cvt_pk_bf16_f32 v109, v116, v117
	v_lshl_add_u64 v[110:111], v[110:111], 0, v[140:141]
	global_store_dwordx4 v[110:111], v[106:109], off
	s_waitcnt vmcnt(15)
	v_lshlrev_b32_e32 v112, 16, v192
	v_and_b32_e32 v113, 0xffff0000, v192
	v_lshlrev_b32_e32 v106, 16, v193
	v_and_b32_e32 v107, 0xffff0000, v193
	v_pk_mul_f32 v[104:105], v[104:105], v[106:107]
	v_lshlrev_b32_e32 v106, 16, v194
	v_and_b32_e32 v107, 0xffff0000, v194
	v_pk_mul_f32 v[106:107], v[98:99], v[106:107]
	v_lshlrev_b32_e32 v98, 16, v195
	v_and_b32_e32 v99, 0xffff0000, v195
	v_pk_mul_f32 v[102:103], v[102:103], v[112:113]
	v_pk_mul_f32 v[108:109], v[100:101], v[98:99]
	v_cvt_pk_bf16_f32 v98, v102, v103
	v_cvt_pk_bf16_f32 v99, v104, v105
	v_cvt_pk_bf16_f32 v100, v106, v107
	v_cvt_pk_bf16_f32 v101, v108, v109
	v_or_b32_e32 v102, 32, v142
	global_store_dwordx4 v[110:111], v[98:101], off offset:256
	v_ashrrev_i32_e32 v103, 31, v102
	s_nop 0
	v_mad_i64_i32 v[98:99], s[0:1], v102, s68, v[144:145]
	v_lshl_add_u64 v[104:105], v[98:99], 0, v[140:141]
	s_waitcnt vmcnt(15)
; #define LAS __attribute__((address_space(3)))
; __device__ __forceinline__ unsigned cvt_pk_bf16(float lo, float hi) { f32x2_t v = {lo, hi}; bf16x2_t b = __builtin_convertvector(v, bf16x2_t); return __builtin_bit_cast(unsigned, b); }
; __device__ __forceinline__ float bflo(unsigned w) { return __uint_as_float(w << 16); }
; __device__ __forceinline__ float bfhi(unsigned w) { return __uint_as_float(w & 0xffff0000u); }
; __device__ __forceinline__ float sigm(float x) { return __builtin_amdgcn_rcpf(1.0f + __expf(-x)); }
;     __device__ __forceinline__ void operator()(AccRef acc, const pg8::Unit& u, int, int, int, int) const {
;     ...
;                 const int row = row0 + ai * 128 + m * 16; float rs = 1.f;
;                 if (MODE == 1 || MODE == 4) rs = ((const LAS float*)((LAS unsigned char*)g_lds + pg8::RSL_OFF))[wid * 128 + ai * 64 + m * 16 + fr];
; #pragma unroll
;                 for (int bj = 0; bj < 2; ++bj) {
;                     const int col = col0 + bj * 128; float o[8];
; #pragma unroll
;                     for (int n = 0; n < 2; ++n)
; #pragma unroll
;                         for (int j = 0; j < 4; ++j) o[n * 4 + j] = acc[ai][bj][m][n][j] * rs;
;                     if (sg) {
; #pragma unroll
;                         for (int j = 0; j < 8; ++j) o[j] = sigm(o[j]); }
;                     if (MODE == 2 || MODE == 3) {
;                         const v4u x = *(const v4u*)(a1 + (size_t)row * ld1 + col);
;                         float xf[8] = {bflo(x.x), bfhi(x.x), bflo(x.y), bfhi(x.y), bflo(x.z), bfhi(x.z), bflo(x.w), bfhi(x.w)};
;                         if (MODE == 2) {
; #pragma unroll
;                             for (int j = 0; j < 8; ++j) o[j] *= xf[j]; }
;                         else { const v4u y = *(const v4u*)(a2 + (size_t)row * ld2 + col);
;                             float yf[8] = {bflo(y.x), bfhi(y.x), bflo(y.y), bfhi(y.y), bflo(y.z), bfhi(y.z), bflo(y.w), bfhi(y.w)};
; #pragma unroll
;                             for (int j = 0; j < 8; ++j) o[j] = xf[j] + yf[j] * o[j]; }
;                     }
;                     v4u w; w.x = cvt_pk_bf16(o[0], o[1]); w.y = cvt_pk_bf16(o[2], o[3]); w.z = cvt_pk_bf16(o[4], o[5]); w.w = cvt_pk_bf16(o[6], o[7]);
;                     *(v4u*)(O + (size_t)row * ldo + col) = w;
	v_lshlrev_b32_e32 v106, 16, v196
	v_and_b32_e32 v107, 0xffff0000, v196
	v_lshlrev_b32_e32 v98, 16, v197
	v_and_b32_e32 v99, 0xffff0000, v197
	v_pk_mul_f32 v[96:97], v[96:97], v[98:99]
	v_lshlrev_b32_e32 v98, 16, v198
	v_and_b32_e32 v99, 0xffff0000, v198
	v_pk_mul_f32 v[94:95], v[94:95], v[106:107]
	v_pk_mul_f32 v[98:99], v[90:91], v[98:99]
	v_lshlrev_b32_e32 v90, 16, v199
	v_and_b32_e32 v91, 0xffff0000, v199
	v_pk_mul_f32 v[100:101], v[92:93], v[90:91]
	v_cvt_pk_bf16_f32 v90, v94, v95
	v_lshlrev_b64 v[94:95], 11, v[102:103]
	v_lshl_add_u64 v[94:95], s[76:77], 0, v[94:95]
	v_cvt_pk_bf16_f32 v91, v96, v97
	v_cvt_pk_bf16_f32 v92, v98, v99
	v_cvt_pk_bf16_f32 v93, v100, v101
	v_lshl_add_u64 v[94:95], v[94:95], 0, v[140:141]
	global_store_dwordx4 v[94:95], v[90:93], off
	s_waitcnt vmcnt(15)
	v_lshlrev_b32_e32 v96, 16, v200
	v_and_b32_e32 v97, 0xffff0000, v200
	v_lshlrev_b32_e32 v90, 16, v201
	v_and_b32_e32 v91, 0xffff0000, v201
	v_pk_mul_f32 v[88:89], v[88:89], v[90:91]
	v_lshlrev_b32_e32 v90, 16, v202
	v_and_b32_e32 v91, 0xffff0000, v202
	v_pk_mul_f32 v[90:91], v[82:83], v[90:91]
	v_lshlrev_b32_e32 v82, 16, v203
	v_and_b32_e32 v83, 0xffff0000, v203
	v_pk_mul_f32 v[86:87], v[86:87], v[96:97]
	v_pk_mul_f32 v[92:93], v[84:85], v[82:83]
	v_cvt_pk_bf16_f32 v82, v86, v87
	v_cvt_pk_bf16_f32 v83, v88, v89
	v_cvt_pk_bf16_f32 v84, v90, v91
	v_cvt_pk_bf16_f32 v85, v92, v93
	v_or_b32_e32 v86, 48, v142
	global_store_dwordx4 v[94:95], v[82:85], off offset:256
	v_ashrrev_i32_e32 v87, 31, v86
	s_nop 0
	v_mad_i64_i32 v[82:83], s[0:1], v86, s68, v[144:145]
	v_lshl_add_u64 v[88:89], v[82:83], 0, v[140:141]
	s_waitcnt vmcnt(15)
	v_lshlrev_b32_e32 v90, 16, v204
	v_and_b32_e32 v91, 0xffff0000, v204
	v_lshlrev_b32_e32 v82, 16, v205
	v_and_b32_e32 v83, 0xffff0000, v205
	v_pk_mul_f32 v[80:81], v[80:81], v[82:83]
	v_lshlrev_b32_e32 v82, 16, v206
	v_and_b32_e32 v83, 0xffff0000, v206
	v_pk_mul_f32 v[78:79], v[78:79], v[90:91]
	v_pk_mul_f32 v[82:83], v[74:75], v[82:83]
	v_lshlrev_b32_e32 v74, 16, v207
	v_and_b32_e32 v75, 0xffff0000, v207
	v_pk_mul_f32 v[84:85], v[76:77], v[74:75]
	v_cvt_pk_bf16_f32 v74, v78, v79
	v_lshlrev_b64 v[78:79], 11, v[86:87]
	v_lshl_add_u64 v[78:79], s[76:77], 0, v[78:79]
	v_cvt_pk_bf16_f32 v75, v80, v81
	v_cvt_pk_bf16_f32 v76, v82, v83
	v_cvt_pk_bf16_f32 v77, v84, v85
	v_lshl_add_u64 v[78:79], v[78:79], 0, v[140:141]
	global_store_dwordx4 v[78:79], v[74:77], off
	s_waitcnt vmcnt(15)
	v_lshlrev_b32_e32 v80, 16, v208
	v_and_b32_e32 v81, 0xffff0000, v208
	v_lshlrev_b32_e32 v74, 16, v209
	v_and_b32_e32 v75, 0xffff0000, v209
	v_pk_mul_f32 v[72:73], v[72:73], v[74:75]
	v_lshlrev_b32_e32 v74, 16, v210
	v_and_b32_e32 v75, 0xffff0000, v210
	v_pk_mul_f32 v[74:75], v[66:67], v[74:75]
	v_lshlrev_b32_e32 v66, 16, v211
	v_and_b32_e32 v67, 0xffff0000, v211
	v_pk_mul_f32 v[70:71], v[70:71], v[80:81]
	v_pk_mul_f32 v[76:77], v[68:69], v[66:67]
	v_cvt_pk_bf16_f32 v66, v70, v71
	v_cvt_pk_bf16_f32 v67, v72, v73
	v_cvt_pk_bf16_f32 v68, v74, v75
	v_cvt_pk_bf16_f32 v69, v76, v77
	v_add_u32_e32 v70, 0x80, v142
	global_store_dwordx4 v[78:79], v[66:69], off offset:256
	v_ashrrev_i32_e32 v71, 31, v70
	s_nop 0
	v_mad_i64_i32 v[66:67], s[0:1], v70, s68, v[144:145]
	v_lshl_add_u64 v[72:73], v[66:67], 0, v[140:141]
	s_waitcnt vmcnt(15)
	v_lshlrev_b32_e32 v74, 16, v212
	v_and_b32_e32 v75, 0xffff0000, v212
	v_lshlrev_b32_e32 v66, 16, v213
	v_and_b32_e32 v67, 0xffff0000, v213
	v_pk_mul_f32 v[64:65], v[64:65], v[66:67]
	v_lshlrev_b32_e32 v66, 16, v214
	v_and_b32_e32 v67, 0xffff0000, v214
	v_pk_mul_f32 v[62:63], v[62:63], v[74:75]
	v_pk_mul_f32 v[66:67], v[58:59], v[66:67]
	v_lshlrev_b32_e32 v58, 16, v215
	v_and_b32_e32 v59, 0xffff0000, v215
	v_pk_mul_f32 v[68:69], v[60:61], v[58:59]
	v_cvt_pk_bf16_f32 v58, v62, v63
	v_lshlrev_b64 v[62:63], 11, v[70:71]
	v_lshl_add_u64 v[62:63], s[76:77], 0, v[62:63]
	v_cvt_pk_bf16_f32 v59, v64, v65
	v_cvt_pk_bf16_f32 v60, v66, v67
	v_cvt_pk_bf16_f32 v61, v68, v69
	v_lshl_add_u64 v[62:63], v[62:63], 0, v[140:141]
	global_store_dwordx4 v[62:63], v[58:61], off
	s_waitcnt vmcnt(15)
	v_lshlrev_b32_e32 v64, 16, v216
	v_and_b32_e32 v65, 0xffff0000, v216
	v_lshlrev_b32_e32 v58, 16, v217
	v_and_b32_e32 v59, 0xffff0000, v217
	v_pk_mul_f32 v[56:57], v[56:57], v[58:59]
	v_lshlrev_b32_e32 v58, 16, v218
	v_and_b32_e32 v59, 0xffff0000, v218
	v_pk_mul_f32 v[58:59], v[50:51], v[58:59]
	v_lshlrev_b32_e32 v50, 16, v219
	v_and_b32_e32 v51, 0xffff0000, v219
	v_pk_mul_f32 v[54:55], v[54:55], v[64:65]
	v_pk_mul_f32 v[60:61], v[52:53], v[50:51]
	v_cvt_pk_bf16_f32 v50, v54, v55
	v_cvt_pk_bf16_f32 v51, v56, v57
	v_cvt_pk_bf16_f32 v52, v58, v59
	v_cvt_pk_bf16_f32 v53, v60, v61
	v_add_u32_e32 v54, 0x90, v142
	global_store_dwordx4 v[62:63], v[50:53], off offset:256
	v_ashrrev_i32_e32 v55, 31, v54
	s_nop 0
	v_mad_i64_i32 v[50:51], s[0:1], v54, s68, v[144:145]
	v_lshl_add_u64 v[56:57], v[50:51], 0, v[140:141]
	s_waitcnt vmcnt(15)
; #define LAS __attribute__((address_space(3)))
; template <class Epi, bool ALIGN_EPI>
; __device__ __forceinline__ void gemm_phase(LAS unsigned char* lds, const Gemm g, const StaticOrder& S, const Epi& E) {
;     ...
;         if (!has_next) break;
; #pragma unroll
;         for (int a = 0; a < 2; ++a)
; #pragma unroll
;             for (int b = 0; b < 2; ++b)
; #pragma unroll
;                 for (int m = 0; m < 4; ++m)
; #pragma unroll
;                     for (int n = 0; n < 2; ++n) acc[a][b][m][n] = (f32x4){0.f, 0.f, 0.f, 0.f};
;         cur = nxt; cA = nA; cB = nB; ++ui;
;         if constexpr (ALIGN_EPI) { if (wr == 1) PG8_BAR; }
;     __device__ __forceinline__ void operator()(AccRef acc, const pg8::Unit& u, int, int, int, int) const {
;     ...
;                 const int row = row0 + ai * 128 + m * 16; float rs = 1.f;
;                 if (MODE == 1 || MODE == 4) rs = ((const LAS float*)((LAS unsigned char*)g_lds + pg8::RSL_OFF))[wid * 128 + ai * 64 + m * 16 + fr];
; #pragma unroll
;                 for (int bj = 0; bj < 2; ++bj) {
;                     const int col = col0 + bj * 128; float o[8];
; #pragma unroll
;                     for (int n = 0; n < 2; ++n)
; #pragma unroll
;                         for (int j = 0; j < 4; ++j) o[n * 4 + j] = acc[ai][bj][m][n][j] * rs;
;                     if (sg) {
; #pragma unroll
;                         for (int j = 0; j < 8; ++j) o[j] = sigm(o[j]); }
;                     if (MODE == 2 || MODE == 3) {
;                         const v4u x = *(const v4u*)(a1 + (size_t)row * ld1 + col);
;                         float xf[8] = {bflo(x.x), bfhi(x.x), bflo(x.y), bfhi(x.y), bflo(x.z), bfhi(x.z), bflo(x.w), bfhi(x.w)};
;                         if (MODE == 2) {
; #pragma unroll
;                             for (int j = 0; j < 8; ++j) o[j] *= xf[j]; }
;                         else { const v4u y = *(const v4u*)(a2 + (size_t)row * ld2 + col);
;                             float yf[8] = {bflo(y.x), bfhi(y.x), bflo(y.y), bfhi(y.y), bflo(y.z), bfhi(y.z), bflo(y.w), bfhi(y.w)};
; #pragma unroll
;                             for (int j = 0; j < 8; ++j) o[j] = xf[j] + yf[j] * o[j]; }
;                     }
;                     v4u w; w.x = cvt_pk_bf16(o[0], o[1]); w.y = cvt_pk_bf16(o[2], o[3]); w.z = cvt_pk_bf16(o[4], o[5]); w.w = cvt_pk_bf16(o[6], o[7]);
;                     *(v4u*)(O + (size_t)row * ldo + col) = w;
	v_lshlrev_b32_e32 v58, 16, v220
	v_and_b32_e32 v59, 0xffff0000, v220
	v_lshlrev_b32_e32 v50, 16, v221
	v_and_b32_e32 v51, 0xffff0000, v221
	v_pk_mul_f32 v[48:49], v[48:49], v[50:51]
	v_lshlrev_b32_e32 v50, 16, v222
	v_and_b32_e32 v51, 0xffff0000, v222
	v_pk_mul_f32 v[46:47], v[46:47], v[58:59]
	v_pk_mul_f32 v[50:51], v[42:43], v[50:51]
	v_lshlrev_b32_e32 v42, 16, v223
	v_and_b32_e32 v43, 0xffff0000, v223
	v_pk_mul_f32 v[52:53], v[44:45], v[42:43]
	v_cvt_pk_bf16_f32 v42, v46, v47
	v_lshlrev_b64 v[46:47], 11, v[54:55]
	v_lshl_add_u64 v[46:47], s[76:77], 0, v[46:47]
	v_cvt_pk_bf16_f32 v43, v48, v49
	v_cvt_pk_bf16_f32 v44, v50, v51
	v_cvt_pk_bf16_f32 v45, v52, v53
	v_lshl_add_u64 v[46:47], v[46:47], 0, v[140:141]
	global_store_dwordx4 v[46:47], v[42:45], off
	s_waitcnt vmcnt(15)
	v_lshlrev_b32_e32 v48, 16, v224
	v_and_b32_e32 v49, 0xffff0000, v224
	v_lshlrev_b32_e32 v42, 16, v225
	v_and_b32_e32 v43, 0xffff0000, v225
	v_pk_mul_f32 v[40:41], v[40:41], v[42:43]
	v_lshlrev_b32_e32 v42, 16, v226
	v_and_b32_e32 v43, 0xffff0000, v226
	v_pk_mul_f32 v[42:43], v[34:35], v[42:43]
	v_lshlrev_b32_e32 v34, 16, v227
	v_and_b32_e32 v35, 0xffff0000, v227
	v_pk_mul_f32 v[38:39], v[38:39], v[48:49]
	v_pk_mul_f32 v[44:45], v[36:37], v[34:35]
	v_cvt_pk_bf16_f32 v34, v38, v39
	v_cvt_pk_bf16_f32 v35, v40, v41
	v_cvt_pk_bf16_f32 v36, v42, v43
	v_cvt_pk_bf16_f32 v37, v44, v45
	v_add_u32_e32 v38, 0xa0, v142
	global_store_dwordx4 v[46:47], v[34:37], off offset:256
	v_ashrrev_i32_e32 v39, 31, v38
	s_nop 0
	v_mad_i64_i32 v[34:35], s[0:1], v38, s68, v[144:145]
	v_lshl_add_u64 v[40:41], v[34:35], 0, v[140:141]
	s_waitcnt vmcnt(15)
	v_lshlrev_b32_e32 v42, 16, v228
	v_and_b32_e32 v43, 0xffff0000, v228
	v_lshlrev_b32_e32 v34, 16, v229
	v_and_b32_e32 v35, 0xffff0000, v229
	v_pk_mul_f32 v[32:33], v[32:33], v[34:35]
	v_lshlrev_b32_e32 v34, 16, v230
	v_and_b32_e32 v35, 0xffff0000, v230
	v_pk_mul_f32 v[30:31], v[30:31], v[42:43]
	v_pk_mul_f32 v[34:35], v[26:27], v[34:35]
	v_lshlrev_b32_e32 v26, 16, v231
	v_and_b32_e32 v27, 0xffff0000, v231
	v_pk_mul_f32 v[36:37], v[28:29], v[26:27]
	v_cvt_pk_bf16_f32 v26, v30, v31
	v_lshlrev_b64 v[30:31], 11, v[38:39]
	v_lshl_add_u64 v[30:31], s[76:77], 0, v[30:31]
	v_cvt_pk_bf16_f32 v27, v32, v33
	v_cvt_pk_bf16_f32 v28, v34, v35
	v_cvt_pk_bf16_f32 v29, v36, v37
	v_lshl_add_u64 v[30:31], v[30:31], 0, v[140:141]
	global_store_dwordx4 v[30:31], v[26:29], off
	s_waitcnt vmcnt(15)
	v_lshlrev_b32_e32 v32, 16, v232
	v_and_b32_e32 v33, 0xffff0000, v232
	v_lshlrev_b32_e32 v26, 16, v233
	v_and_b32_e32 v27, 0xffff0000, v233
	v_pk_mul_f32 v[24:25], v[24:25], v[26:27]
	v_lshlrev_b32_e32 v26, 16, v234
	v_and_b32_e32 v27, 0xffff0000, v234
	v_pk_mul_f32 v[26:27], v[18:19], v[26:27]
	v_lshlrev_b32_e32 v18, 16, v235
	v_and_b32_e32 v19, 0xffff0000, v235
	v_pk_mul_f32 v[22:23], v[22:23], v[32:33]
	v_pk_mul_f32 v[28:29], v[20:21], v[18:19]
	v_cvt_pk_bf16_f32 v18, v22, v23
	v_cvt_pk_bf16_f32 v19, v24, v25
	v_cvt_pk_bf16_f32 v20, v26, v27
	v_cvt_pk_bf16_f32 v21, v28, v29
	v_add_u32_e32 v22, 0xb0, v142
	global_store_dwordx4 v[30:31], v[18:21], off offset:256
	v_ashrrev_i32_e32 v23, 31, v22
	s_nop 0
	v_mad_i64_i32 v[18:19], s[0:1], v22, s68, v[144:145]
	v_lshl_add_u64 v[24:25], v[18:19], 0, v[140:141]
	s_mov_b64 s[0:1], -1
	s_waitcnt vmcnt(15)
	v_lshlrev_b32_e32 v26, 16, v236
	v_and_b32_e32 v27, 0xffff0000, v236
	v_lshlrev_b32_e32 v18, 16, v237
	v_and_b32_e32 v19, 0xffff0000, v237
	v_pk_mul_f32 v[16:17], v[16:17], v[18:19]
	v_lshlrev_b32_e32 v18, 16, v238
	v_and_b32_e32 v19, 0xffff0000, v238
	v_pk_mul_f32 v[14:15], v[14:15], v[26:27]
	v_pk_mul_f32 v[18:19], v[10:11], v[18:19]
	v_lshlrev_b32_e32 v10, 16, v239
	v_and_b32_e32 v11, 0xffff0000, v239
	v_pk_mul_f32 v[20:21], v[12:13], v[10:11]
	v_cvt_pk_bf16_f32 v10, v14, v15
	v_lshlrev_b64 v[14:15], 11, v[22:23]
	v_lshl_add_u64 v[14:15], s[76:77], 0, v[14:15]
	v_cvt_pk_bf16_f32 v11, v16, v17
	v_cvt_pk_bf16_f32 v12, v18, v19
	v_cvt_pk_bf16_f32 v13, v20, v21
	v_lshl_add_u64 v[14:15], v[14:15], 0, v[140:141]
	global_store_dwordx4 v[14:15], v[10:13], off
	s_waitcnt vmcnt(15)
	v_lshlrev_b32_e32 v16, 16, v240
	v_and_b32_e32 v17, 0xffff0000, v240
	v_lshlrev_b32_e32 v10, 16, v241
	v_and_b32_e32 v11, 0xffff0000, v241
	v_pk_mul_f32 v[8:9], v[8:9], v[10:11]
	v_lshlrev_b32_e32 v10, 16, v242
	v_and_b32_e32 v11, 0xffff0000, v242
	v_pk_mul_f32 v[10:11], v[2:3], v[10:11]
	v_lshlrev_b32_e32 v2, 16, v243
	v_and_b32_e32 v3, 0xffff0000, v243
	v_pk_mul_f32 v[6:7], v[6:7], v[16:17]
	v_pk_mul_f32 v[12:13], v[4:5], v[2:3]
	v_cvt_pk_bf16_f32 v2, v6, v7
	v_cvt_pk_bf16_f32 v3, v8, v9
	v_cvt_pk_bf16_f32 v4, v10, v11
	v_cvt_pk_bf16_f32 v5, v12, v13
	global_store_dwordx4 v[14:15], v[2:5], off offset:256
	s_cbranch_vccnz .LBB0_404
	s_andn2_b64 vcc, exec, s[10:11]
	s_cbranch_vccnz .LBB0_403
	s_barrier
	s_branch .LBB0_403

; __device__ __forceinline__ unsigned cvt_pk_bf16(float lo, float hi) { f32x2_t v = {lo, hi}; bf16x2_t b = __builtin_convertvector(v, bf16x2_t); return __builtin_bit_cast(unsigned, b); }
; __device__ __forceinline__ float bflo(unsigned w) { return __uint_as_float(w << 16); }
; __device__ __forceinline__ float bfhi(unsigned w) { return __uint_as_float(w & 0xffff0000u); }
;     __device__ __forceinline__ void operator()(AccRef acc, const pg8::Unit& u, int, int, int, int) const {
;     ...
;                     if (MODE == 2 || MODE == 3) {
;                         const v4u x = *(const v4u*)(a1 + (size_t)row * ld1 + col);
;                         float xf[8] = {bflo(x.x), bfhi(x.x), bflo(x.y), bfhi(x.y), bflo(x.z), bfhi(x.z), bflo(x.w), bfhi(x.w)};
;                         if (MODE == 2) {
; #pragma unroll
;                             for (int j = 0; j < 8; ++j) o[j] *= xf[j]; }
;                         else { const v4u y = *(const v4u*)(a2 + (size_t)row * ld2 + col);
;                             float yf[8] = {bflo(y.x), bfhi(y.x), bflo(y.y), bfhi(y.y), bflo(y.z), bfhi(y.z), bflo(y.w), bfhi(y.w)};
; #pragma unroll
;                             for (int j = 0; j < 8; ++j) o[j] = xf[j] + yf[j] * o[j]; }
;                     }
;                     v4u w; w.x = cvt_pk_bf16(o[0], o[1]); w.y = cvt_pk_bf16(o[2], o[3]); w.z = cvt_pk_bf16(o[4], o[5]); w.w = cvt_pk_bf16(o[6], o[7]);
;                     *(v4u*)(O + (size_t)row * ldo + col) = w;
.LBB0_443:
	v_mov_b32_e32 v141, v155
	s_lshl_b32 s1, s38, 8
	v_readfirstlane_b32 s0, v141
	s_ashr_i32 s2, s0, 2
	s_lshr_b32 s0, s0, 1
	s_andn2_b32 s2, s2, 63
	s_lshl_b32 s3, s39, 8
	s_and_b32 s0, s0, 0x60
	v_lshrrev_b32_e32 v140, 1, v141
	v_and_or_b32 v141, v141, 15, s1
	s_or_b32 s0, s0, s3
	v_add_u32_e32 v144, s2, v141
	v_and_or_b32 v140, v140, 24, s0
	v_ashrrev_i32_e32 v145, 31, v144
	v_lshlrev_b64 v[142:143], 11, v[144:145]
	v_ashrrev_i32_e32 v141, 31, v140
	v_lshl_add_u64 v[142:143], s[76:77], 0, v[142:143]
	v_lshlrev_b64 v[140:141], 1, v[140:141]
	v_lshl_add_u64 v[152:153], v[142:143], 0, v[140:141]
	v_mov_b64_e32 v[142:143], s[10:11]
	v_mad_i64_i32 v[156:157], s[0:1], v144, s68, v[142:143]
	v_lshl_add_u64 v[160:161], v[156:157], 0, v[140:141]
	v_mov_b32_e32 v248, v152
	v_mov_b32_e32 v249, v153
	v_mov_b32_e32 v250, v160
	v_mov_b32_e32 v251, v161
	global_load_dwordx4 v[180:183], v[248:249], off
	global_load_dwordx4 v[184:187], v[250:251], off
	global_load_dwordx4 v[188:191], v[248:249], off offset:256
	global_load_dwordx4 v[192:195], v[250:251], off offset:256
	v_mov_b32_e32 v244, 0x8000
	v_mov_b32_e32 v245, 0
	v_lshl_add_u64 v[246:247], v[248:249], 0, v[244:245]
	v_mov_b32_e32 v244, 0x2c000
	v_mov_b32_e32 v245, 0
	v_lshl_add_u64 v[252:253], v[250:251], 0, v[244:245]
	global_load_dwordx4 v[196:199], v[246:247], off
	global_load_dwordx4 v[200:203], v[252:253], off
	global_load_dwordx4 v[204:207], v[246:247], off offset:256
	global_load_dwordx4 v[208:211], v[252:253], off offset:256
	v_mov_b32_e32 v244, 0x10000
	v_mov_b32_e32 v245, 0
	v_lshl_add_u64 v[246:247], v[248:249], 0, v[244:245]
	v_mov_b32_e32 v244, 0x58000
	v_mov_b32_e32 v245, 0
	v_lshl_add_u64 v[252:253], v[250:251], 0, v[244:245]
	global_load_dwordx4 v[212:215], v[246:247], off
	global_load_dwordx4 v[216:219], v[252:253], off
	global_load_dwordx4 v[220:223], v[246:247], off offset:256
	global_load_dwordx4 v[224:227], v[252:253], off offset:256
	v_mov_b32_e32 v244, 0x18000
	v_mov_b32_e32 v245, 0
	v_lshl_add_u64 v[246:247], v[248:249], 0, v[244:245]
	v_mov_b32_e32 v244, 0x84000
	v_mov_b32_e32 v245, 0
	v_lshl_add_u64 v[252:253], v[250:251], 0, v[244:245]
	global_load_dwordx4 v[228:231], v[246:247], off
	global_load_dwordx4 v[232:235], v[252:253], off
	global_load_dwordx4 v[236:239], v[246:247], off offset:256
	global_load_dwordx4 v[240:243], v[252:253], off offset:256
	v_readlane_b32 s0, v254, 43
	v_readlane_b32 s1, v254, 44
	s_and_b64 vcc, exec, s[6:7]
	s_waitcnt vmcnt(14)
	v_lshlrev_b32_e32 v162, 16, v180
	v_and_b32_e32 v163, 0xffff0000, v180
	v_lshlrev_b32_e32 v170, 16, v184
	v_and_b32_e32 v171, 0xffff0000, v184
	v_lshlrev_b32_e32 v148, 16, v181
	v_and_b32_e32 v149, 0xffff0000, v181
	v_lshlrev_b32_e32 v156, 16, v185
	v_and_b32_e32 v157, 0xffff0000, v185
	v_pk_fma_f32 v[128:129], v[128:129], v[156:157], v[148:149]
	v_lshlrev_b32_e32 v148, 16, v182
	v_and_b32_e32 v149, 0xffff0000, v182
	v_lshlrev_b32_e32 v156, 16, v186
	v_and_b32_e32 v157, 0xffff0000, v186
	v_pk_fma_f32 v[126:127], v[126:127], v[170:171], v[162:163]
	v_pk_fma_f32 v[122:123], v[122:123], v[156:157], v[148:149]
	v_lshlrev_b32_e32 v148, 16, v183
	v_and_b32_e32 v149, 0xffff0000, v183
	v_lshlrev_b32_e32 v150, 16, v187
	v_and_b32_e32 v151, 0xffff0000, v187
	v_pk_fma_f32 v[148:149], v[124:125], v[150:151], v[148:149]
	v_cvt_pk_bf16_f32 v124, v126, v127
	v_cvt_pk_bf16_f32 v126, v122, v123
	v_mov_b64_e32 v[122:123], s[0:1]
	v_cvt_pk_bf16_f32 v125, v128, v129
	v_mad_i64_i32 v[128:129], s[0:1], v144, s68, v[122:123]
	v_cvt_pk_bf16_f32 v127, v148, v149
	v_lshl_add_u64 v[128:129], v[128:129], 0, v[140:141]
	global_store_dwordx4 v[128:129], v[124:127], off
	v_mov_b32_e32 v244, 0x40000
	v_mov_b32_e32 v245, 0
	v_lshl_add_u64 v[246:247], v[248:249], 0, v[244:245]
	v_mov_b32_e32 v244, 0x160000
	v_mov_b32_e32 v245, 0
	v_lshl_add_u64 v[252:253], v[250:251], 0, v[244:245]
	global_load_dwordx4 v[180:183], v[246:247], off
	global_load_dwordx4 v[184:187], v[252:253], off
	s_nop 0
	s_waitcnt vmcnt(16)
	v_lshlrev_b32_e32 v152, 16, v188
	v_and_b32_e32 v153, 0xffff0000, v188
	s_waitcnt vmcnt(15)
	v_lshlrev_b32_e32 v156, 16, v192
	v_and_b32_e32 v157, 0xffff0000, v192
	v_lshlrev_b32_e32 v124, 16, v189
	v_and_b32_e32 v125, 0xffff0000, v189
	v_lshlrev_b32_e32 v148, 16, v193
	v_and_b32_e32 v149, 0xffff0000, v193
	v_pk_fma_f32 v[120:121], v[120:121], v[148:149], v[124:125]
	v_lshlrev_b32_e32 v124, 16, v190
	v_and_b32_e32 v125, 0xffff0000, v190
	v_lshlrev_b32_e32 v148, 16, v194
	v_and_b32_e32 v149, 0xffff0000, v194
	v_pk_fma_f32 v[124:125], v[114:115], v[148:149], v[124:125]
	v_lshlrev_b32_e32 v114, 16, v191
	v_and_b32_e32 v115, 0xffff0000, v191
	v_lshlrev_b32_e32 v126, 16, v195
	v_and_b32_e32 v127, 0xffff0000, v195
	v_pk_fma_f32 v[118:119], v[118:119], v[156:157], v[152:153]
	v_pk_fma_f32 v[126:127], v[116:117], v[126:127], v[114:115]
	v_cvt_pk_bf16_f32 v114, v118, v119
	v_cvt_pk_bf16_f32 v115, v120, v121
	v_cvt_pk_bf16_f32 v116, v124, v125
	v_cvt_pk_bf16_f32 v117, v126, v127
	global_store_dwordx4 v[128:129], v[114:117], off offset:256
	s_nop 1
	v_or_b32_e32 v114, 16, v144
	v_ashrrev_i32_e32 v115, 31, v114
	v_lshlrev_b64 v[116:117], 11, v[114:115]
	v_lshl_add_u64 v[116:117], s[76:77], 0, v[116:117]
	v_mad_i64_i32 v[118:119], s[0:1], v114, s68, v[142:143]
	v_lshl_add_u64 v[116:117], v[116:117], 0, v[140:141]
	v_lshl_add_u64 v[118:119], v[118:119], 0, v[140:141]
	v_mov_b32_e32 v244, 0x40000
	v_mov_b32_e32 v245, 0
	v_lshl_add_u64 v[246:247], v[248:249], 0, v[244:245]
	v_mov_b32_e32 v244, 0x160000
	v_mov_b32_e32 v245, 0
	v_lshl_add_u64 v[252:253], v[250:251], 0, v[244:245]
	global_load_dwordx4 v[188:191], v[246:247], off offset:256
	global_load_dwordx4 v[192:195], v[252:253], off offset:256
	s_waitcnt vmcnt(17)
; __device__ __forceinline__ unsigned cvt_pk_bf16(float lo, float hi) { f32x2_t v = {lo, hi}; bf16x2_t b = __builtin_convertvector(v, bf16x2_t); return __builtin_bit_cast(unsigned, b); }
; __device__ __forceinline__ float bflo(unsigned w) { return __uint_as_float(w << 16); }
; __device__ __forceinline__ float bfhi(unsigned w) { return __uint_as_float(w & 0xffff0000u); }
;     __device__ __forceinline__ void operator()(AccRef acc, const pg8::Unit& u, int, int, int, int) const {
;     ...
;                     if (MODE == 2 || MODE == 3) {
;                         const v4u x = *(const v4u*)(a1 + (size_t)row * ld1 + col);
;                         float xf[8] = {bflo(x.x), bfhi(x.x), bflo(x.y), bfhi(x.y), bflo(x.z), bfhi(x.z), bflo(x.w), bfhi(x.w)};
;                         if (MODE == 2) {
; #pragma unroll
;                             for (int j = 0; j < 8; ++j) o[j] *= xf[j]; }
;                         else { const v4u y = *(const v4u*)(a2 + (size_t)row * ld2 + col);
;                             float yf[8] = {bflo(y.x), bfhi(y.x), bflo(y.y), bfhi(y.y), bflo(y.z), bfhi(y.z), bflo(y.w), bfhi(y.w)};
; #pragma unroll
;                             for (int j = 0; j < 8; ++j) o[j] = xf[j] + yf[j] * o[j]; }
;                     }
;                     v4u w; w.x = cvt_pk_bf16(o[0], o[1]); w.y = cvt_pk_bf16(o[2], o[3]); w.z = cvt_pk_bf16(o[4], o[5]); w.w = cvt_pk_bf16(o[6], o[7]);
;                     *(v4u*)(O + (size_t)row * ldo + col) = w;
	v_lshlrev_b32_e32 v120, 16, v196
	v_and_b32_e32 v121, 0xffff0000, v196
	s_waitcnt vmcnt(16)
	v_lshlrev_b32_e32 v128, 16, v200
	v_and_b32_e32 v129, 0xffff0000, v200
	v_pk_fma_f32 v[110:111], v[110:111], v[128:129], v[120:121]
	v_lshlrev_b32_e32 v120, 16, v197
	v_and_b32_e32 v121, 0xffff0000, v197
	v_lshlrev_b32_e32 v124, 16, v201
	v_and_b32_e32 v125, 0xffff0000, v201
	v_pk_fma_f32 v[112:113], v[112:113], v[124:125], v[120:121]
	v_lshlrev_b32_e32 v120, 16, v198
	v_and_b32_e32 v121, 0xffff0000, v198
	v_lshlrev_b32_e32 v124, 16, v202
	v_and_b32_e32 v125, 0xffff0000, v202
	v_pk_fma_f32 v[120:121], v[106:107], v[124:125], v[120:121]
	v_lshlrev_b32_e32 v106, 16, v199
	v_and_b32_e32 v107, 0xffff0000, v199
	v_lshlrev_b32_e32 v124, 16, v203
	v_and_b32_e32 v125, 0xffff0000, v203
	v_pk_fma_f32 v[124:125], v[108:109], v[124:125], v[106:107]
	v_cvt_pk_bf16_f32 v106, v110, v111
	v_mad_i64_i32 v[110:111], s[0:1], v114, s68, v[122:123]
	v_cvt_pk_bf16_f32 v107, v112, v113
	v_cvt_pk_bf16_f32 v108, v120, v121
	v_cvt_pk_bf16_f32 v109, v124, v125
	v_lshl_add_u64 v[114:115], v[110:111], 0, v[140:141]
	global_store_dwordx4 v[114:115], v[106:109], off
	v_mov_b32_e32 v244, 0x48000
	v_mov_b32_e32 v245, 0
	v_lshl_add_u64 v[246:247], v[248:249], 0, v[244:245]
	v_mov_b32_e32 v244, 0x18c000
	v_mov_b32_e32 v245, 0
	v_lshl_add_u64 v[252:253], v[250:251], 0, v[244:245]
	global_load_dwordx4 v[196:199], v[246:247], off
	global_load_dwordx4 v[200:203], v[252:253], off
	s_nop 0
	s_waitcnt vmcnt(18)
	v_lshlrev_b32_e32 v116, 16, v204
	v_and_b32_e32 v117, 0xffff0000, v204
	s_waitcnt vmcnt(17)
	v_lshlrev_b32_e32 v118, 16, v208
	v_and_b32_e32 v119, 0xffff0000, v208
	v_lshlrev_b32_e32 v106, 16, v205
	v_and_b32_e32 v107, 0xffff0000, v205
	v_lshlrev_b32_e32 v110, 16, v209
	v_and_b32_e32 v111, 0xffff0000, v209
	v_pk_fma_f32 v[104:105], v[104:105], v[110:111], v[106:107]
	v_lshlrev_b32_e32 v106, 16, v206
	v_and_b32_e32 v107, 0xffff0000, v206
	v_lshlrev_b32_e32 v110, 16, v210
	v_and_b32_e32 v111, 0xffff0000, v210
	v_pk_fma_f32 v[106:107], v[98:99], v[110:111], v[106:107]
	v_lshlrev_b32_e32 v98, 16, v207
	v_and_b32_e32 v99, 0xffff0000, v207
	v_lshlrev_b32_e32 v108, 16, v211
	v_and_b32_e32 v109, 0xffff0000, v211
	v_pk_fma_f32 v[102:103], v[102:103], v[118:119], v[116:117]
	v_pk_fma_f32 v[108:109], v[100:101], v[108:109], v[98:99]
	v_cvt_pk_bf16_f32 v98, v102, v103
	v_cvt_pk_bf16_f32 v99, v104, v105
	v_cvt_pk_bf16_f32 v100, v106, v107
	v_cvt_pk_bf16_f32 v101, v108, v109
	global_store_dwordx4 v[114:115], v[98:101], off offset:256
	s_nop 1
	v_or_b32_e32 v98, 32, v144
	v_ashrrev_i32_e32 v99, 31, v98
	v_lshlrev_b64 v[100:101], 11, v[98:99]
	v_lshl_add_u64 v[100:101], s[76:77], 0, v[100:101]
	v_mad_i64_i32 v[106:107], s[0:1], v98, s68, v[142:143]
	v_lshl_add_u64 v[100:101], v[100:101], 0, v[140:141]
	v_lshl_add_u64 v[110:111], v[106:107], 0, v[140:141]
	v_mov_b32_e32 v244, 0x48000
	v_mov_b32_e32 v245, 0
	v_lshl_add_u64 v[246:247], v[248:249], 0, v[244:245]
	v_mov_b32_e32 v244, 0x18c000
	v_mov_b32_e32 v245, 0
	v_lshl_add_u64 v[252:253], v[250:251], 0, v[244:245]
	global_load_dwordx4 v[204:207], v[246:247], off offset:256
	global_load_dwordx4 v[208:211], v[252:253], off offset:256
	s_waitcnt vmcnt(19)
	v_lshlrev_b32_e32 v112, 16, v212
	v_and_b32_e32 v113, 0xffff0000, v212
	s_waitcnt vmcnt(18)
	v_lshlrev_b32_e32 v114, 16, v216
	v_and_b32_e32 v115, 0xffff0000, v216
	v_lshlrev_b32_e32 v102, 16, v213
	v_and_b32_e32 v103, 0xffff0000, v213
	v_lshlrev_b32_e32 v106, 16, v217
	v_and_b32_e32 v107, 0xffff0000, v217
	v_pk_fma_f32 v[96:97], v[96:97], v[106:107], v[102:103]
	v_lshlrev_b32_e32 v102, 16, v214
	v_and_b32_e32 v103, 0xffff0000, v214
	v_lshlrev_b32_e32 v106, 16, v218
	v_and_b32_e32 v107, 0xffff0000, v218
	v_pk_fma_f32 v[94:95], v[94:95], v[114:115], v[112:113]
	v_pk_fma_f32 v[102:103], v[90:91], v[106:107], v[102:103]
	v_lshlrev_b32_e32 v90, 16, v215
	v_and_b32_e32 v91, 0xffff0000, v215
	v_lshlrev_b32_e32 v104, 16, v219
	v_and_b32_e32 v105, 0xffff0000, v219
	v_pk_fma_f32 v[104:105], v[92:93], v[104:105], v[90:91]
	v_cvt_pk_bf16_f32 v90, v94, v95
	v_mad_i64_i32 v[94:95], s[0:1], v98, s68, v[122:123]
	v_cvt_pk_bf16_f32 v91, v96, v97
	v_cvt_pk_bf16_f32 v92, v102, v103
	v_cvt_pk_bf16_f32 v93, v104, v105
	v_lshl_add_u64 v[98:99], v[94:95], 0, v[140:141]
	global_store_dwordx4 v[98:99], v[90:93], off
	v_mov_b32_e32 v244, 0x50000
	v_mov_b32_e32 v245, 0
	v_lshl_add_u64 v[246:247], v[248:249], 0, v[244:245]
	v_mov_b32_e32 v244, 0x1b8000
	v_mov_b32_e32 v245, 0
	v_lshl_add_u64 v[252:253], v[250:251], 0, v[244:245]
	global_load_dwordx4 v[212:215], v[246:247], off
	global_load_dwordx4 v[216:219], v[252:253], off
	s_nop 0
	s_waitcnt vmcnt(20)
	v_lshlrev_b32_e32 v100, 16, v220
	v_and_b32_e32 v101, 0xffff0000, v220
	s_waitcnt vmcnt(19)
	v_lshlrev_b32_e32 v102, 16, v224
	v_and_b32_e32 v103, 0xffff0000, v224
	v_lshlrev_b32_e32 v90, 16, v221
	v_and_b32_e32 v91, 0xffff0000, v221
	v_lshlrev_b32_e32 v94, 16, v225
	v_and_b32_e32 v95, 0xffff0000, v225
	v_pk_fma_f32 v[88:89], v[88:89], v[94:95], v[90:91]
	v_lshlrev_b32_e32 v90, 16, v222
	v_and_b32_e32 v91, 0xffff0000, v222
	v_lshlrev_b32_e32 v94, 16, v226
	v_and_b32_e32 v95, 0xffff0000, v226
	v_pk_fma_f32 v[90:91], v[82:83], v[94:95], v[90:91]
	v_lshlrev_b32_e32 v82, 16, v223
	v_and_b32_e32 v83, 0xffff0000, v223
	v_lshlrev_b32_e32 v92, 16, v227
	v_and_b32_e32 v93, 0xffff0000, v227
	v_pk_fma_f32 v[86:87], v[86:87], v[102:103], v[100:101]
	v_pk_fma_f32 v[92:93], v[84:85], v[92:93], v[82:83]
	v_cvt_pk_bf16_f32 v82, v86, v87
	v_cvt_pk_bf16_f32 v83, v88, v89
	v_cvt_pk_bf16_f32 v84, v90, v91
	v_cvt_pk_bf16_f32 v85, v92, v93
	global_store_dwordx4 v[98:99], v[82:85], off offset:256
	s_nop 1
	v_or_b32_e32 v82, 48, v144
	v_ashrrev_i32_e32 v83, 31, v82
	v_lshlrev_b64 v[84:85], 11, v[82:83]
	v_lshl_add_u64 v[84:85], s[76:77], 0, v[84:85]
	v_mad_i64_i32 v[86:87], s[0:1], v82, s68, v[142:143]
	v_lshl_add_u64 v[84:85], v[84:85], 0, v[140:141]
	v_lshl_add_u64 v[86:87], v[86:87], 0, v[140:141]
	v_mov_b32_e32 v244, 0x50000
	v_mov_b32_e32 v245, 0
	v_lshl_add_u64 v[246:247], v[248:249], 0, v[244:245]
	v_mov_b32_e32 v244, 0x1b8000
	v_mov_b32_e32 v245, 0
	v_lshl_add_u64 v[252:253], v[250:251], 0, v[244:245]
	global_load_dwordx4 v[220:223], v[246:247], off offset:256
	global_load_dwordx4 v[224:227], v[252:253], off offset:256
	s_waitcnt vmcnt(21)
; __device__ __forceinline__ unsigned cvt_pk_bf16(float lo, float hi) { f32x2_t v = {lo, hi}; bf16x2_t b = __builtin_convertvector(v, bf16x2_t); return __builtin_bit_cast(unsigned, b); }
; __device__ __forceinline__ float bflo(unsigned w) { return __uint_as_float(w << 16); }
; __device__ __forceinline__ float bfhi(unsigned w) { return __uint_as_float(w & 0xffff0000u); }
;     __device__ __forceinline__ void operator()(AccRef acc, const pg8::Unit& u, int, int, int, int) const {
;     ...
;                     if (MODE == 2 || MODE == 3) {
;                         const v4u x = *(const v4u*)(a1 + (size_t)row * ld1 + col);
;                         float xf[8] = {bflo(x.x), bfhi(x.x), bflo(x.y), bfhi(x.y), bflo(x.z), bfhi(x.z), bflo(x.w), bfhi(x.w)};
;                         if (MODE == 2) {
; #pragma unroll
;                             for (int j = 0; j < 8; ++j) o[j] *= xf[j]; }
;                         else { const v4u y = *(const v4u*)(a2 + (size_t)row * ld2 + col);
;                             float yf[8] = {bflo(y.x), bfhi(y.x), bflo(y.y), bfhi(y.y), bflo(y.z), bfhi(y.z), bflo(y.w), bfhi(y.w)};
; #pragma unroll
;                             for (int j = 0; j < 8; ++j) o[j] = xf[j] + yf[j] * o[j]; }
;                     }
;                     v4u w; w.x = cvt_pk_bf16(o[0], o[1]); w.y = cvt_pk_bf16(o[2], o[3]); w.z = cvt_pk_bf16(o[4], o[5]); w.w = cvt_pk_bf16(o[6], o[7]);
;                     *(v4u*)(O + (size_t)row * ldo + col) = w;
	v_lshlrev_b32_e32 v96, 16, v228
	v_and_b32_e32 v97, 0xffff0000, v228
	s_waitcnt vmcnt(20)
	v_lshlrev_b32_e32 v98, 16, v232
	v_and_b32_e32 v99, 0xffff0000, v232
	v_lshlrev_b32_e32 v88, 16, v229
	v_and_b32_e32 v89, 0xffff0000, v229
	v_lshlrev_b32_e32 v92, 16, v233
	v_and_b32_e32 v93, 0xffff0000, v233
	v_pk_fma_f32 v[80:81], v[80:81], v[92:93], v[88:89]
	v_lshlrev_b32_e32 v88, 16, v230
	v_and_b32_e32 v89, 0xffff0000, v230
	v_lshlrev_b32_e32 v92, 16, v234
	v_and_b32_e32 v93, 0xffff0000, v234
	v_pk_fma_f32 v[78:79], v[78:79], v[98:99], v[96:97]
	v_pk_fma_f32 v[88:89], v[74:75], v[92:93], v[88:89]
	v_lshlrev_b32_e32 v74, 16, v231
	v_and_b32_e32 v75, 0xffff0000, v231
	v_lshlrev_b32_e32 v90, 16, v235
	v_and_b32_e32 v91, 0xffff0000, v235
	v_pk_fma_f32 v[90:91], v[76:77], v[90:91], v[74:75]
	v_cvt_pk_bf16_f32 v74, v78, v79
	v_mad_i64_i32 v[78:79], s[0:1], v82, s68, v[122:123]
	v_cvt_pk_bf16_f32 v75, v80, v81
	v_cvt_pk_bf16_f32 v76, v88, v89
	v_cvt_pk_bf16_f32 v77, v90, v91
	v_lshl_add_u64 v[82:83], v[78:79], 0, v[140:141]
	global_store_dwordx4 v[82:83], v[74:77], off
	v_mov_b32_e32 v244, 0x58000
	v_mov_b32_e32 v245, 0
	v_lshl_add_u64 v[246:247], v[248:249], 0, v[244:245]
	v_mov_b32_e32 v244, 0x1e4000
	v_mov_b32_e32 v245, 0
	v_lshl_add_u64 v[252:253], v[250:251], 0, v[244:245]
	global_load_dwordx4 v[228:231], v[246:247], off
	global_load_dwordx4 v[232:235], v[252:253], off
	s_nop 0
	s_waitcnt vmcnt(22)
	v_lshlrev_b32_e32 v84, 16, v236
	v_and_b32_e32 v85, 0xffff0000, v236
	s_waitcnt vmcnt(21)
	v_lshlrev_b32_e32 v86, 16, v240
	v_and_b32_e32 v87, 0xffff0000, v240
	v_lshlrev_b32_e32 v74, 16, v237
	v_and_b32_e32 v75, 0xffff0000, v237
	v_lshlrev_b32_e32 v78, 16, v241
	v_and_b32_e32 v79, 0xffff0000, v241
	v_pk_fma_f32 v[72:73], v[72:73], v[78:79], v[74:75]
	v_lshlrev_b32_e32 v74, 16, v238
	v_and_b32_e32 v75, 0xffff0000, v238
	v_lshlrev_b32_e32 v78, 16, v242
	v_and_b32_e32 v79, 0xffff0000, v242
	v_pk_fma_f32 v[74:75], v[66:67], v[78:79], v[74:75]
	v_lshlrev_b32_e32 v66, 16, v239
	v_and_b32_e32 v67, 0xffff0000, v239
	v_lshlrev_b32_e32 v76, 16, v243
	v_and_b32_e32 v77, 0xffff0000, v243
	v_pk_fma_f32 v[70:71], v[70:71], v[86:87], v[84:85]
	v_pk_fma_f32 v[76:77], v[68:69], v[76:77], v[66:67]
	v_cvt_pk_bf16_f32 v66, v70, v71
	v_cvt_pk_bf16_f32 v67, v72, v73
	v_cvt_pk_bf16_f32 v68, v74, v75
	v_cvt_pk_bf16_f32 v69, v76, v77
	global_store_dwordx4 v[82:83], v[66:69], off offset:256
	s_nop 1
	v_add_u32_e32 v66, 0x80, v144
	v_ashrrev_i32_e32 v67, 31, v66
	v_lshlrev_b64 v[68:69], 11, v[66:67]
	v_lshl_add_u64 v[68:69], s[76:77], 0, v[68:69]
	v_mad_i64_i32 v[74:75], s[0:1], v66, s68, v[142:143]
	v_lshl_add_u64 v[68:69], v[68:69], 0, v[140:141]
	v_lshl_add_u64 v[78:79], v[74:75], 0, v[140:141]
	v_mov_b32_e32 v244, 0x58000
	v_mov_b32_e32 v245, 0
	v_lshl_add_u64 v[246:247], v[248:249], 0, v[244:245]
	v_mov_b32_e32 v244, 0x1e4000
	v_mov_b32_e32 v245, 0
	v_lshl_add_u64 v[252:253], v[250:251], 0, v[244:245]
	global_load_dwordx4 v[236:239], v[246:247], off offset:256
	global_load_dwordx4 v[240:243], v[252:253], off offset:256
	s_waitcnt vmcnt(22)
	v_lshlrev_b32_e32 v80, 16, v180
	v_and_b32_e32 v81, 0xffff0000, v180
	s_waitcnt vmcnt(21)
	v_lshlrev_b32_e32 v82, 16, v184
	v_and_b32_e32 v83, 0xffff0000, v184
	v_lshlrev_b32_e32 v70, 16, v181
	v_and_b32_e32 v71, 0xffff0000, v181
	v_lshlrev_b32_e32 v74, 16, v185
	v_and_b32_e32 v75, 0xffff0000, v185
	v_pk_fma_f32 v[64:65], v[64:65], v[74:75], v[70:71]
	v_lshlrev_b32_e32 v70, 16, v182
	v_and_b32_e32 v71, 0xffff0000, v182
	v_lshlrev_b32_e32 v74, 16, v186
	v_and_b32_e32 v75, 0xffff0000, v186
	v_pk_fma_f32 v[62:63], v[62:63], v[82:83], v[80:81]
	v_pk_fma_f32 v[70:71], v[58:59], v[74:75], v[70:71]
	v_lshlrev_b32_e32 v58, 16, v183
	v_and_b32_e32 v59, 0xffff0000, v183
	v_lshlrev_b32_e32 v72, 16, v187
	v_and_b32_e32 v73, 0xffff0000, v187
	v_pk_fma_f32 v[72:73], v[60:61], v[72:73], v[58:59]
	v_cvt_pk_bf16_f32 v58, v62, v63
	v_mad_i64_i32 v[62:63], s[0:1], v66, s68, v[122:123]
	v_cvt_pk_bf16_f32 v59, v64, v65
	v_cvt_pk_bf16_f32 v60, v70, v71
	v_cvt_pk_bf16_f32 v61, v72, v73
	v_lshl_add_u64 v[66:67], v[62:63], 0, v[140:141]
	global_store_dwordx4 v[66:67], v[58:61], off
	s_nop 0
	s_waitcnt vmcnt(20)
	v_lshlrev_b32_e32 v68, 16, v188
	v_and_b32_e32 v69, 0xffff0000, v188
	s_waitcnt vmcnt(19)
	v_lshlrev_b32_e32 v70, 16, v192
	v_and_b32_e32 v71, 0xffff0000, v192
	v_lshlrev_b32_e32 v58, 16, v189
	v_and_b32_e32 v59, 0xffff0000, v189
	v_lshlrev_b32_e32 v62, 16, v193
	v_and_b32_e32 v63, 0xffff0000, v193
	v_pk_fma_f32 v[56:57], v[56:57], v[62:63], v[58:59]
	v_lshlrev_b32_e32 v58, 16, v190
	v_and_b32_e32 v59, 0xffff0000, v190
	v_lshlrev_b32_e32 v62, 16, v194
	v_and_b32_e32 v63, 0xffff0000, v194
	v_pk_fma_f32 v[58:59], v[50:51], v[62:63], v[58:59]
	v_lshlrev_b32_e32 v50, 16, v191
	v_and_b32_e32 v51, 0xffff0000, v191
	v_lshlrev_b32_e32 v60, 16, v195
	v_and_b32_e32 v61, 0xffff0000, v195
	v_pk_fma_f32 v[54:55], v[54:55], v[70:71], v[68:69]
	v_pk_fma_f32 v[60:61], v[52:53], v[60:61], v[50:51]
	v_cvt_pk_bf16_f32 v50, v54, v55
	v_cvt_pk_bf16_f32 v51, v56, v57
	v_cvt_pk_bf16_f32 v52, v58, v59
	v_cvt_pk_bf16_f32 v53, v60, v61
	global_store_dwordx4 v[66:67], v[50:53], off offset:256
	s_nop 1
	v_add_u32_e32 v50, 0x90, v144
	v_ashrrev_i32_e32 v51, 31, v50
	v_lshlrev_b64 v[52:53], 11, v[50:51]
	v_lshl_add_u64 v[52:53], s[76:77], 0, v[52:53]
	v_mad_i64_i32 v[54:55], s[0:1], v50, s68, v[142:143]
	v_lshl_add_u64 v[52:53], v[52:53], 0, v[140:141]
	v_lshl_add_u64 v[54:55], v[54:55], 0, v[140:141]
	s_waitcnt vmcnt(18)
	v_lshlrev_b32_e32 v64, 16, v196
	v_and_b32_e32 v65, 0xffff0000, v196
	s_waitcnt vmcnt(17)
; __device__ __forceinline__ unsigned cvt_pk_bf16(float lo, float hi) { f32x2_t v = {lo, hi}; bf16x2_t b = __builtin_convertvector(v, bf16x2_t); return __builtin_bit_cast(unsigned, b); }
; __device__ __forceinline__ float bflo(unsigned w) { return __uint_as_float(w << 16); }
; __device__ __forceinline__ float bfhi(unsigned w) { return __uint_as_float(w & 0xffff0000u); }
; #define PG8_BAR __builtin_amdgcn_s_barrier()
; template <class Epi, bool ALIGN_EPI>
; __device__ __forceinline__ void gemm_phase(LAS unsigned char* lds, const Gemm g, const StaticOrder& S, const Epi& E) {
;     ...
;         if (!has_next) break;
; #pragma unroll
;         for (int a = 0; a < 2; ++a)
; #pragma unroll
;             for (int b = 0; b < 2; ++b)
; #pragma unroll
;                 for (int m = 0; m < 4; ++m)
; #pragma unroll
;                     for (int n = 0; n < 2; ++n) acc[a][b][m][n] = (f32x4){0.f, 0.f, 0.f, 0.f};
;         cur = nxt; cA = nA; cB = nB; ++ui;
;         if constexpr (ALIGN_EPI) { if (wr == 1) PG8_BAR; }
;     __device__ __forceinline__ void operator()(AccRef acc, const pg8::Unit& u, int, int, int, int) const {
;     ...
;                     if (MODE == 2 || MODE == 3) {
;                         const v4u x = *(const v4u*)(a1 + (size_t)row * ld1 + col);
;                         float xf[8] = {bflo(x.x), bfhi(x.x), bflo(x.y), bfhi(x.y), bflo(x.z), bfhi(x.z), bflo(x.w), bfhi(x.w)};
;                         if (MODE == 2) {
; #pragma unroll
;                             for (int j = 0; j < 8; ++j) o[j] *= xf[j]; }
;                         else { const v4u y = *(const v4u*)(a2 + (size_t)row * ld2 + col);
;                             float yf[8] = {bflo(y.x), bfhi(y.x), bflo(y.y), bfhi(y.y), bflo(y.z), bfhi(y.z), bflo(y.w), bfhi(y.w)};
; #pragma unroll
;                             for (int j = 0; j < 8; ++j) o[j] = xf[j] + yf[j] * o[j]; }
;                     }
;                     v4u w; w.x = cvt_pk_bf16(o[0], o[1]); w.y = cvt_pk_bf16(o[2], o[3]); w.z = cvt_pk_bf16(o[4], o[5]); w.w = cvt_pk_bf16(o[6], o[7]);
;                     *(v4u*)(O + (size_t)row * ldo + col) = w;
	v_lshlrev_b32_e32 v66, 16, v200
	v_and_b32_e32 v67, 0xffff0000, v200
	v_lshlrev_b32_e32 v56, 16, v197
	v_and_b32_e32 v57, 0xffff0000, v197
	v_lshlrev_b32_e32 v60, 16, v201
	v_and_b32_e32 v61, 0xffff0000, v201
	v_pk_fma_f32 v[48:49], v[48:49], v[60:61], v[56:57]
	v_lshlrev_b32_e32 v56, 16, v198
	v_and_b32_e32 v57, 0xffff0000, v198
	v_lshlrev_b32_e32 v60, 16, v202
	v_and_b32_e32 v61, 0xffff0000, v202
	v_pk_fma_f32 v[46:47], v[46:47], v[66:67], v[64:65]
	v_pk_fma_f32 v[56:57], v[42:43], v[60:61], v[56:57]
	v_lshlrev_b32_e32 v42, 16, v199
	v_and_b32_e32 v43, 0xffff0000, v199
	v_lshlrev_b32_e32 v58, 16, v203
	v_and_b32_e32 v59, 0xffff0000, v203
	v_pk_fma_f32 v[58:59], v[44:45], v[58:59], v[42:43]
	v_cvt_pk_bf16_f32 v42, v46, v47
	v_mad_i64_i32 v[46:47], s[0:1], v50, s68, v[122:123]
	v_cvt_pk_bf16_f32 v43, v48, v49
	v_cvt_pk_bf16_f32 v44, v56, v57
	v_cvt_pk_bf16_f32 v45, v58, v59
	v_lshl_add_u64 v[50:51], v[46:47], 0, v[140:141]
	global_store_dwordx4 v[50:51], v[42:45], off
	s_nop 0
	s_waitcnt vmcnt(16)
	v_lshlrev_b32_e32 v52, 16, v204
	v_and_b32_e32 v53, 0xffff0000, v204
	s_waitcnt vmcnt(15)
	v_lshlrev_b32_e32 v54, 16, v208
	v_and_b32_e32 v55, 0xffff0000, v208
	v_lshlrev_b32_e32 v42, 16, v205
	v_and_b32_e32 v43, 0xffff0000, v205
	v_lshlrev_b32_e32 v46, 16, v209
	v_and_b32_e32 v47, 0xffff0000, v209
	v_pk_fma_f32 v[40:41], v[40:41], v[46:47], v[42:43]
	v_lshlrev_b32_e32 v42, 16, v206
	v_and_b32_e32 v43, 0xffff0000, v206
	v_lshlrev_b32_e32 v46, 16, v210
	v_and_b32_e32 v47, 0xffff0000, v210
	v_pk_fma_f32 v[42:43], v[34:35], v[46:47], v[42:43]
	v_lshlrev_b32_e32 v34, 16, v207
	v_and_b32_e32 v35, 0xffff0000, v207
	v_lshlrev_b32_e32 v44, 16, v211
	v_and_b32_e32 v45, 0xffff0000, v211
	v_pk_fma_f32 v[38:39], v[38:39], v[54:55], v[52:53]
	v_pk_fma_f32 v[44:45], v[36:37], v[44:45], v[34:35]
	v_cvt_pk_bf16_f32 v34, v38, v39
	v_cvt_pk_bf16_f32 v35, v40, v41
	v_cvt_pk_bf16_f32 v36, v42, v43
	v_cvt_pk_bf16_f32 v37, v44, v45
	global_store_dwordx4 v[50:51], v[34:37], off offset:256
	s_nop 1
	v_add_u32_e32 v34, 0xa0, v144
	v_ashrrev_i32_e32 v35, 31, v34
	v_lshlrev_b64 v[36:37], 11, v[34:35]
	v_lshl_add_u64 v[36:37], s[76:77], 0, v[36:37]
	v_mad_i64_i32 v[42:43], s[0:1], v34, s68, v[142:143]
	v_lshl_add_u64 v[36:37], v[36:37], 0, v[140:141]
	v_lshl_add_u64 v[46:47], v[42:43], 0, v[140:141]
	s_waitcnt vmcnt(14)
	v_lshlrev_b32_e32 v48, 16, v212
	v_and_b32_e32 v49, 0xffff0000, v212
	s_waitcnt vmcnt(13)
	v_lshlrev_b32_e32 v50, 16, v216
	v_and_b32_e32 v51, 0xffff0000, v216
	v_lshlrev_b32_e32 v38, 16, v213
	v_and_b32_e32 v39, 0xffff0000, v213
	v_lshlrev_b32_e32 v42, 16, v217
	v_and_b32_e32 v43, 0xffff0000, v217
	v_pk_fma_f32 v[32:33], v[32:33], v[42:43], v[38:39]
	v_lshlrev_b32_e32 v38, 16, v214
	v_and_b32_e32 v39, 0xffff0000, v214
	v_lshlrev_b32_e32 v42, 16, v218
	v_and_b32_e32 v43, 0xffff0000, v218
	v_pk_fma_f32 v[30:31], v[30:31], v[50:51], v[48:49]
	v_pk_fma_f32 v[38:39], v[26:27], v[42:43], v[38:39]
	v_lshlrev_b32_e32 v26, 16, v215
	v_and_b32_e32 v27, 0xffff0000, v215
	v_lshlrev_b32_e32 v40, 16, v219
	v_and_b32_e32 v41, 0xffff0000, v219
	v_pk_fma_f32 v[40:41], v[28:29], v[40:41], v[26:27]
	v_cvt_pk_bf16_f32 v26, v30, v31
	v_mad_i64_i32 v[30:31], s[0:1], v34, s68, v[122:123]
	v_cvt_pk_bf16_f32 v27, v32, v33
	v_cvt_pk_bf16_f32 v28, v38, v39
	v_cvt_pk_bf16_f32 v29, v40, v41
	v_lshl_add_u64 v[34:35], v[30:31], 0, v[140:141]
	global_store_dwordx4 v[34:35], v[26:29], off
	s_nop 0
	s_waitcnt vmcnt(12)
	v_lshlrev_b32_e32 v36, 16, v220
	v_and_b32_e32 v37, 0xffff0000, v220
	s_waitcnt vmcnt(11)
	v_lshlrev_b32_e32 v38, 16, v224
	v_and_b32_e32 v39, 0xffff0000, v224
	v_lshlrev_b32_e32 v26, 16, v221
	v_and_b32_e32 v27, 0xffff0000, v221
	v_lshlrev_b32_e32 v30, 16, v225
	v_and_b32_e32 v31, 0xffff0000, v225
	v_pk_fma_f32 v[24:25], v[24:25], v[30:31], v[26:27]
	v_lshlrev_b32_e32 v26, 16, v222
	v_and_b32_e32 v27, 0xffff0000, v222
	v_lshlrev_b32_e32 v30, 16, v226
	v_and_b32_e32 v31, 0xffff0000, v226
	v_pk_fma_f32 v[26:27], v[18:19], v[30:31], v[26:27]
	v_lshlrev_b32_e32 v18, 16, v223
	v_and_b32_e32 v19, 0xffff0000, v223
	v_lshlrev_b32_e32 v28, 16, v227
	v_and_b32_e32 v29, 0xffff0000, v227
	v_pk_fma_f32 v[22:23], v[22:23], v[38:39], v[36:37]
	v_pk_fma_f32 v[28:29], v[20:21], v[28:29], v[18:19]
	v_cvt_pk_bf16_f32 v18, v22, v23
	v_cvt_pk_bf16_f32 v19, v24, v25
	v_cvt_pk_bf16_f32 v20, v26, v27
	v_cvt_pk_bf16_f32 v21, v28, v29
	global_store_dwordx4 v[34:35], v[18:21], off offset:256
	s_nop 1
	v_add_u32_e32 v18, 0xb0, v144
	v_ashrrev_i32_e32 v19, 31, v18
	v_lshlrev_b64 v[20:21], 11, v[18:19]
	v_lshl_add_u64 v[20:21], s[76:77], 0, v[20:21]
	v_mad_i64_i32 v[22:23], s[0:1], v18, s68, v[142:143]
	v_lshl_add_u64 v[20:21], v[20:21], 0, v[140:141]
	v_lshl_add_u64 v[22:23], v[22:23], 0, v[140:141]
	s_waitcnt vmcnt(10)
	v_lshlrev_b32_e32 v32, 16, v228
	v_and_b32_e32 v33, 0xffff0000, v228
	s_waitcnt vmcnt(9)
	v_lshlrev_b32_e32 v34, 16, v232
	v_and_b32_e32 v35, 0xffff0000, v232
	v_lshlrev_b32_e32 v24, 16, v229
	v_and_b32_e32 v25, 0xffff0000, v229
	v_lshlrev_b32_e32 v28, 16, v233
	v_and_b32_e32 v29, 0xffff0000, v233
	v_pk_fma_f32 v[16:17], v[16:17], v[28:29], v[24:25]
	v_lshlrev_b32_e32 v24, 16, v230
	v_and_b32_e32 v25, 0xffff0000, v230
	v_lshlrev_b32_e32 v28, 16, v234
	v_and_b32_e32 v29, 0xffff0000, v234
	v_pk_fma_f32 v[14:15], v[14:15], v[34:35], v[32:33]
	v_pk_fma_f32 v[24:25], v[10:11], v[28:29], v[24:25]
	v_lshlrev_b32_e32 v10, 16, v231
	v_and_b32_e32 v11, 0xffff0000, v231
	v_lshlrev_b32_e32 v26, 16, v235
	v_and_b32_e32 v27, 0xffff0000, v235
	v_pk_fma_f32 v[26:27], v[12:13], v[26:27], v[10:11]
	v_cvt_pk_bf16_f32 v10, v14, v15
	v_mad_i64_i32 v[14:15], s[0:1], v18, s68, v[122:123]
	v_cvt_pk_bf16_f32 v11, v16, v17
	v_cvt_pk_bf16_f32 v12, v24, v25
	v_cvt_pk_bf16_f32 v13, v26, v27
	v_lshl_add_u64 v[18:19], v[14:15], 0, v[140:141]
	global_store_dwordx4 v[18:19], v[10:13], off
	s_nop 0
	s_mov_b64 s[0:1], -1
	s_waitcnt vmcnt(8)
	v_lshlrev_b32_e32 v20, 16, v236
	v_and_b32_e32 v21, 0xffff0000, v236
	s_waitcnt vmcnt(7)
	v_lshlrev_b32_e32 v22, 16, v240
	v_and_b32_e32 v23, 0xffff0000, v240
	v_lshlrev_b32_e32 v10, 16, v237
	v_and_b32_e32 v11, 0xffff0000, v237
	v_lshlrev_b32_e32 v14, 16, v241
	v_and_b32_e32 v15, 0xffff0000, v241
	v_pk_fma_f32 v[8:9], v[8:9], v[14:15], v[10:11]
	v_lshlrev_b32_e32 v10, 16, v238
	v_and_b32_e32 v11, 0xffff0000, v238
	v_lshlrev_b32_e32 v14, 16, v242
	v_and_b32_e32 v15, 0xffff0000, v242
	v_pk_fma_f32 v[10:11], v[2:3], v[14:15], v[10:11]
	v_lshlrev_b32_e32 v2, 16, v239
	v_and_b32_e32 v3, 0xffff0000, v239
	v_lshlrev_b32_e32 v12, 16, v243
	v_and_b32_e32 v13, 0xffff0000, v243
	v_pk_fma_f32 v[6:7], v[6:7], v[22:23], v[20:21]
	v_pk_fma_f32 v[12:13], v[4:5], v[12:13], v[2:3]
	v_cvt_pk_bf16_f32 v2, v6, v7
	v_cvt_pk_bf16_f32 v3, v8, v9
	v_cvt_pk_bf16_f32 v4, v10, v11
	v_cvt_pk_bf16_f32 v5, v12, v13
	global_store_dwordx4 v[18:19], v[2:5], off offset:256
	s_cbranch_vccnz .LBB0_430
	s_andn2_b64 vcc, exec, s[8:9]
	s_cbranch_vccnz .LBB0_429
	s_barrier
	s_branch .LBB0_429
